# as v22 with the attention loop placed 4 bytes later (one s_nop in the entry shim): code placement
# speedup vs baseline: 1.0055x; 1.0009x over previous
; #define SBAR() __builtin_amdgcn_sched_barrier(0)
; __device__ __forceinline__ void attn_unit(const bf16* __restrict__ Qb, const bf16* __restrict__ KN, const bf16* __restrict__ KR, ...
;     ...
;   int rp = 0, rc = 1, rn = 2;
;   for (int j = 1; j + 1 < NT; j += 2) {
;     SBAR(); qkt(pB0, pB1, K_lds + rc * SHM_K, qr, qs, kb);
.Lattn_noprio:
	s_waitcnt lgkmcnt(0)
	s_nop 0
